# plus A/B mixers: permlane32_swap instead of ds_bpermute for cross-half max, unmasked bias path for interior window tiles
# baseline (speedup 1.0000x reference)
; template <int NDB, int NKG>
; __device__ __forceinline__ void softmax_pv(f32x16& s, float& m, float& l, f32x16 (&o)[NDB], const LAS char* vtile, int kg0, int troff) {
;     float rm = fmaxf(s[0], s[1]);
; #pragma unroll
;     for (int r = 2; r < 16; ++r) rm = fmaxf(rm, s[r]);
;     rm = fmaxf(rm, __shfl_xor(rm, 32));
;     const float mn = fmaxf(m, rm);
;     if (__any(rm > m + 8.0f)) {
;         const float alpha = __builtin_amdgcn_exp2f(m - mn);
;         l *= alpha;
; #pragma unroll
;         for (int db = 0; db < NDB; ++db) o[db] = o[db] * alpha;
;         m = mn;
;     }
.LBB0_247:
	s_waitcnt vmcnt(6)
	ds_write_b128 v169, v[68:71]
	ds_write_b128 v170, v[64:67] offset:4096
	s_waitcnt vmcnt(4)
	ds_write_b128 v171, v[76:79]
	ds_write_b128 v172, v[72:75] offset:4096
	s_waitcnt vmcnt(2)
	ds_write_b128 v169, v[84:87] offset:1024
	ds_write_b128 v170, v[80:83] offset:4352
	s_waitcnt vmcnt(0)
	ds_write_b128 v173, v[100:103] offset:1024
	ds_write_b128 v174, v[92:95] offset:4096
	ds_read_b128 v[32:35], v175 offset:4096
	ds_read_b128 v[182:185], v175 offset:5152
	v_cvt_f32_i32_e32 v181, v179
	s_waitcnt lgkmcnt(1)
	v_mfma_f32_32x32x16_bf16 v[32:47], v[32:35], v[48:51], 0
	v_cmp_le_f32_e64 vcc, |v181|, s1
	v_add_f32_e32 v190, 0xc1100000, v181
	v_add_f32_e32 v191, 0xc1200000, v181
	s_waitcnt lgkmcnt(0)
	v_mfma_f32_32x32x16_bf16 v[32:47], v[182:185], v[52:55], v[32:47]
	ds_read_b128 v[182:185], v175 offset:6208
	ds_read_b128 v[186:189], v175 offset:7264
	s_waitcnt lgkmcnt(1)
	v_mfma_f32_32x32x16_bf16 v[32:47], v[182:185], v[56:59], v[32:47]
	v_add_f32_e32 v182, -1.0, v181
	v_add_f32_e32 v183, -2.0, v181
	v_add_f32_e32 v184, 0xc0400000, v181
	v_add_f32_e32 v185, 0xc1000000, v181
	s_waitcnt lgkmcnt(0)
	v_mfma_f32_32x32x16_bf16 v[32:47], v[186:189], v[60:63], v[32:47]
	v_readfirstlane_b32 s100, v179
	s_add_i32 s100, s100, 33
	s_cmp_lt_u32 s100, 67
	s_cbranch_scc0 .Lab_masked_0
	s_nop 7
	v_fma_f32 v32, v177, |v181|, v32
	v_fma_f32 v33, v177, |v182|, v33
	v_fma_f32 v34, v177, |v183|, v34
	v_fma_f32 v35, v177, |v184|, v35
	v_fma_f32 v36, v177, |v185|, v36
	v_fma_f32 v37, v177, |v190|, v37
	v_fma_f32 v38, v177, |v191|, v38
	v_add_f32_e32 v182, 0xc1300000, v181
	v_fma_f32 v39, v177, |v182|, v39
	v_add_f32_e32 v182, 0xc1800000, v181
	v_fma_f32 v40, v177, |v182|, v40
	v_add_f32_e32 v182, 0xc1880000, v181
	v_fma_f32 v41, v177, |v182|, v41
	v_add_f32_e32 v182, 0xc1900000, v181
	v_fma_f32 v42, v177, |v182|, v42
	v_add_f32_e32 v182, 0xc1980000, v181
	v_fma_f32 v43, v177, |v182|, v43
	v_add_f32_e32 v182, 0xc1c00000, v181
	v_fma_f32 v44, v177, |v182|, v44
	v_add_f32_e32 v182, 0xc1c80000, v181
	v_fma_f32 v45, v177, |v182|, v45
	v_add_f32_e32 v182, 0xc1d00000, v181
	v_fma_f32 v46, v177, |v182|, v46
	v_add_f32_e32 v181, 0xc1d80000, v181
	v_fma_f32 v47, v177, |v181|, v47
	v_max_f32_e32 v181, v32, v33
	v_max3_f32 v181, v181, v34, v35
	v_max3_f32 v181, v181, v36, v37
	v_max3_f32 v181, v181, v38, v39
	v_max3_f32 v181, v181, v40, v41
	v_max3_f32 v181, v181, v42, v43
	v_max3_f32 v181, v181, v44, v45
	v_max3_f32 v181, v181, v46, v47
	s_branch .Lab_join_0
.Lab_masked_0:
	s_nop 7
	v_fma_f32 v32, v177, |v181|, v32
	v_fma_f32 v33, v177, |v182|, v33
	v_cndmask_b32_e32 v32, v240, v32, vcc
	v_cmp_le_f32_e64 vcc, |v182|, s1
	v_fma_f32 v34, v177, |v183|, v34
	v_fma_f32 v35, v177, |v184|, v35
	v_cndmask_b32_e32 v33, v240, v33, vcc
	v_cmp_le_f32_e64 vcc, |v183|, s1
	v_fma_f32 v36, v177, |v185|, v36
	v_fma_f32 v37, v177, |v190|, v37
	v_cndmask_b32_e32 v34, v240, v34, vcc
	v_cmp_le_f32_e64 vcc, |v184|, s1
	v_fma_f32 v38, v177, |v191|, v38
	v_add_f32_e32 v182, 0xc1300000, v181
	v_cndmask_b32_e32 v35, v240, v35, vcc
	v_cmp_le_f32_e64 vcc, |v185|, s1
	v_fma_f32 v39, v177, |v182|, v39
	s_nop 0
	v_cndmask_b32_e32 v36, v240, v36, vcc
	v_cmp_le_f32_e64 vcc, |v190|, s1
	s_nop 1
	v_cndmask_b32_e32 v37, v240, v37, vcc
	v_cmp_le_f32_e64 vcc, |v191|, s1
	s_nop 1
	v_cndmask_b32_e32 v38, v240, v38, vcc
	v_cmp_le_f32_e64 vcc, |v182|, s1
	v_add_f32_e32 v182, 0xc1800000, v181
	v_fma_f32 v40, v177, |v182|, v40
	v_cndmask_b32_e32 v39, v240, v39, vcc
	v_cmp_le_f32_e64 vcc, |v182|, s1
	v_add_f32_e32 v182, 0xc1880000, v181
	v_fma_f32 v41, v177, |v182|, v41
	v_cndmask_b32_e32 v40, v240, v40, vcc
	v_cmp_le_f32_e64 vcc, |v182|, s1
	v_add_f32_e32 v182, 0xc1900000, v181
	v_fma_f32 v42, v177, |v182|, v42
	v_cndmask_b32_e32 v41, v240, v41, vcc
	v_cmp_le_f32_e64 vcc, |v182|, s1
	v_add_f32_e32 v182, 0xc1980000, v181
	v_fma_f32 v43, v177, |v182|, v43
	v_cndmask_b32_e32 v42, v240, v42, vcc
	v_cmp_le_f32_e64 vcc, |v182|, s1
	v_add_f32_e32 v182, 0xc1c00000, v181
	v_fma_f32 v44, v177, |v182|, v44
	v_cndmask_b32_e32 v43, v240, v43, vcc
	v_cmp_le_f32_e64 vcc, |v182|, s1
	v_add_f32_e32 v182, 0xc1c80000, v181
	v_fma_f32 v45, v177, |v182|, v45
	v_cndmask_b32_e32 v44, v240, v44, vcc
	v_cmp_le_f32_e64 vcc, |v182|, s1
	v_add_f32_e32 v182, 0xc1d00000, v181
	v_fma_f32 v46, v177, |v182|, v46
	v_cndmask_b32_e32 v45, v240, v45, vcc
	v_cmp_le_f32_e64 vcc, |v182|, s1
	v_add_f32_e32 v181, 0xc1d80000, v181
	v_fma_f32 v47, v177, |v181|, v47
	v_cndmask_b32_e32 v46, v240, v46, vcc
	v_cmp_le_f32_e64 vcc, |v181|, s1
	v_max_f32_e32 v181, v32, v33
	v_max3_f32 v181, v181, v34, v35
	v_max3_f32 v181, v181, v36, v37
	v_max3_f32 v181, v181, v38, v39
	v_max3_f32 v181, v181, v40, v41
	v_max3_f32 v181, v181, v42, v43
	v_cndmask_b32_e32 v47, v240, v47, vcc
	v_max3_f32 v181, v181, v44, v45
	v_max3_f32 v181, v181, v46, v47
.Lab_join_0:
	v_mov_b32_e32 v182, v181
	s_nop 1
	v_permlane32_swap_b32_e32 v181, v182
	v_max_f32_e32 v181, v181, v182
	v_add_f32_e32 v182, 0x41000000, v180
	v_cmp_gt_f32_e32 vcc, v181, v182
	s_cbranch_vccz .LBB0_249
	v_max_f32_e32 v181, v181, v181
	v_max_f32_e32 v182, v180, v180
	v_max_f32_e32 v181, v182, v181
	v_sub_f32_e32 v180, v180, v181
	v_exp_f32_e32 v180, v180
	s_nop 0
	v_mul_f32_e32 v135, v135, v180
	v_pk_mul_f32 v[14:15], v[14:15], v[180:181] op_sel_hi:[1,0]
	v_pk_mul_f32 v[12:13], v[12:13], v[180:181] op_sel_hi:[1,0]
	v_pk_mul_f32 v[10:11], v[10:11], v[180:181] op_sel_hi:[1,0]
	v_pk_mul_f32 v[8:9], v[8:9], v[180:181] op_sel_hi:[1,0]
	v_pk_mul_f32 v[6:7], v[6:7], v[180:181] op_sel_hi:[1,0]
	v_pk_mul_f32 v[4:5], v[4:5], v[180:181] op_sel_hi:[1,0]
	v_pk_mul_f32 v[2:3], v[2:3], v[180:181] op_sel_hi:[1,0]
	v_pk_mul_f32 v[0:1], v[0:1], v[180:181] op_sel_hi:[1,0]
	v_pk_mul_f32 v[30:31], v[30:31], v[180:181] op_sel_hi:[1,0]
	v_pk_mul_f32 v[28:29], v[28:29], v[180:181] op_sel_hi:[1,0]
	v_pk_mul_f32 v[26:27], v[26:27], v[180:181] op_sel_hi:[1,0]
	v_pk_mul_f32 v[24:25], v[24:25], v[180:181] op_sel_hi:[1,0]
	v_pk_mul_f32 v[22:23], v[22:23], v[180:181] op_sel_hi:[1,0]
	v_pk_mul_f32 v[20:21], v[20:21], v[180:181] op_sel_hi:[1,0]
	v_pk_mul_f32 v[18:19], v[18:19], v[180:181] op_sel_hi:[1,0]
	v_pk_mul_f32 v[16:17], v[16:17], v[180:181] op_sel_hi:[1,0]
	v_mov_b32_e32 v180, v181

; template <int NDB, int NKG>
; __device__ __forceinline__ void softmax_pv(f32x16& s, float& m, float& l, f32x16 (&o)[NDB], const LAS char* vtile, int kg0, int troff) {
;     ...
;     for (int r = 0; r < 16; ++r) { s[r] = __builtin_amdgcn_exp2f(s[r] - m); ps += s[r]; }
;     l += ps;
.LBB0_251:
	v_add_f32_e32 v32, 0, v32
	v_add_f32_e32 v32, v33, v32
	v_add_f32_e32 v32, v34, v32
	v_add_f32_e32 v32, v35, v32
	v_add_f32_e32 v32, v36, v32
	v_add_f32_e32 v32, v37, v32
	v_add_f32_e32 v32, v38, v32
	v_add_f32_e32 v32, v39, v32
	v_add_f32_e32 v32, v40, v32
	v_add_f32_e32 v32, v41, v32
	v_add_f32_e32 v32, v42, v32
	v_add_f32_e32 v32, v43, v32
	v_add_f32_e32 v32, v44, v32
	v_add_f32_e32 v32, v45, v32
	v_add_f32_e32 v32, v46, v32
	v_add_f32_e32 v32, v47, v32
	s_add_i32 vcc_lo, s47, -3
	s_cmp_ge_i32 vcc_lo, s46
	v_add_f32_e32 v135, v135, v32
	s_cbranch_scc1 .LBB0_246
	ds_write_b128 v169, v[96:99]
	ds_write_b128 v170, v[88:91] offset:4096
	ds_write_b128 v171, v[108:111]
	ds_write_b128 v172, v[104:107] offset:4096
	ds_write_b128 v169, v[116:119] offset:1024
	ds_write_b128 v170, v[112:115] offset:4352
	ds_write_b128 v173, v[124:127] offset:1024
	ds_write_b128 v174, v[120:123] offset:4096
	ds_read_b128 v[32:35], v175 offset:4096
	ds_read_b128 v[182:185], v175 offset:5152
	ds_read_b128 v[186:189], v175 offset:7264
	v_subrev_u32_e32 v181, 32, v179
	s_waitcnt lgkmcnt(2)
	v_mfma_f32_32x32x16_bf16 v[32:47], v[32:35], v[48:51], 0
	v_cvt_f32_i32_e32 v181, v181
	v_cmp_le_f32_e64 vcc, |v181|, s1
	v_add_f32_e32 v190, 0xc1100000, v181
	v_add_f32_e32 v191, 0xc1200000, v181
	s_waitcnt lgkmcnt(1)
	v_mfma_f32_32x32x16_bf16 v[32:47], v[182:185], v[52:55], v[32:47]
	ds_read_b128 v[182:185], v175 offset:6208
	s_waitcnt lgkmcnt(0)
	v_mfma_f32_32x32x16_bf16 v[32:47], v[182:185], v[56:59], v[32:47]
	v_add_f32_e32 v182, -1.0, v181
	v_add_f32_e32 v183, -2.0, v181
	v_add_f32_e32 v184, 0xc0400000, v181
	v_add_f32_e32 v185, 0xc1000000, v181
	v_mfma_f32_32x32x16_bf16 v[32:47], v[186:189], v[60:63], v[32:47]
	v_readfirstlane_b32 s100, v179
	s_add_i32 s100, s100, 1
	s_cmp_lt_u32 s100, 67
	s_cbranch_scc0 .Lab_masked_1
	s_nop 7
	v_fma_f32 v32, v177, |v181|, v32
	v_fma_f32 v33, v177, |v182|, v33
	v_fma_f32 v34, v177, |v183|, v34
	v_fma_f32 v35, v177, |v184|, v35
	v_fma_f32 v36, v177, |v185|, v36
	v_fma_f32 v37, v177, |v190|, v37
	v_fma_f32 v38, v177, |v191|, v38
	v_add_f32_e32 v182, 0xc1300000, v181
	v_fma_f32 v39, v177, |v182|, v39
	v_add_f32_e32 v182, 0xc1800000, v181
	v_fma_f32 v40, v177, |v182|, v40
	v_add_f32_e32 v182, 0xc1880000, v181
	v_fma_f32 v41, v177, |v182|, v41
	v_add_f32_e32 v182, 0xc1900000, v181
	v_fma_f32 v42, v177, |v182|, v42
	v_add_f32_e32 v182, 0xc1980000, v181
	v_fma_f32 v43, v177, |v182|, v43
	v_add_f32_e32 v182, 0xc1c00000, v181
	v_fma_f32 v44, v177, |v182|, v44
	v_add_f32_e32 v182, 0xc1c80000, v181
	v_fma_f32 v45, v177, |v182|, v45
	v_add_f32_e32 v182, 0xc1d00000, v181
	v_fma_f32 v46, v177, |v182|, v46
	v_add_f32_e32 v181, 0xc1d80000, v181
	v_fma_f32 v47, v177, |v181|, v47
	v_max_f32_e32 v181, v32, v33
	v_max3_f32 v181, v181, v34, v35
	v_max3_f32 v181, v181, v36, v37
	v_max3_f32 v181, v181, v38, v39
	v_max3_f32 v181, v181, v40, v41
	v_max3_f32 v181, v181, v42, v43
	v_max3_f32 v181, v181, v44, v45
	v_max3_f32 v181, v181, v46, v47
	s_branch .Lab_join_1

; template <int NDB, int NKG>
; __device__ __forceinline__ void softmax_pv(f32x16& s, float& m, float& l, f32x16 (&o)[NDB], const LAS char* vtile, int kg0, int troff) {
;     ...
;     rm = fmaxf(rm, __shfl_xor(rm, 32));
;     const float mn = fmaxf(m, rm);
;     if (__any(rm > m + 8.0f)) {
;         const float alpha = __builtin_amdgcn_exp2f(m - mn);
;         l *= alpha;
; #pragma unroll
;         for (int db = 0; db < NDB; ++db) o[db] = o[db] * alpha;
;         m = mn;
;     }
.Lab_join_1:
	v_mov_b32_e32 v182, v181
	s_nop 1
	v_permlane32_swap_b32_e32 v181, v182
	v_max_f32_e32 v181, v181, v182
	v_add_f32_e32 v182, 0x41000000, v180
	v_cmp_gt_f32_e32 vcc, v181, v182
	s_cbranch_vccz .LBB0_254
	v_max_f32_e32 v181, v181, v181
	v_max_f32_e32 v182, v180, v180
	v_max_f32_e32 v181, v182, v181
	v_sub_f32_e32 v180, v180, v181
	v_exp_f32_e32 v180, v180
	s_nop 0
	v_mul_f32_e32 v135, v135, v180
	v_pk_mul_f32 v[30:31], v[30:31], v[180:181] op_sel_hi:[1,0]
	v_pk_mul_f32 v[28:29], v[28:29], v[180:181] op_sel_hi:[1,0]
	v_pk_mul_f32 v[26:27], v[26:27], v[180:181] op_sel_hi:[1,0]
	v_pk_mul_f32 v[24:25], v[24:25], v[180:181] op_sel_hi:[1,0]
	v_pk_mul_f32 v[22:23], v[22:23], v[180:181] op_sel_hi:[1,0]
	v_pk_mul_f32 v[20:21], v[20:21], v[180:181] op_sel_hi:[1,0]
	v_pk_mul_f32 v[18:19], v[18:19], v[180:181] op_sel_hi:[1,0]
	v_pk_mul_f32 v[16:17], v[16:17], v[180:181] op_sel_hi:[1,0]
	v_pk_mul_f32 v[14:15], v[14:15], v[180:181] op_sel_hi:[1,0]
	v_pk_mul_f32 v[12:13], v[12:13], v[180:181] op_sel_hi:[1,0]
	v_pk_mul_f32 v[10:11], v[10:11], v[180:181] op_sel_hi:[1,0]
	v_pk_mul_f32 v[8:9], v[8:9], v[180:181] op_sel_hi:[1,0]
	v_pk_mul_f32 v[6:7], v[6:7], v[180:181] op_sel_hi:[1,0]
	v_pk_mul_f32 v[4:5], v[4:5], v[180:181] op_sel_hi:[1,0]
	v_pk_mul_f32 v[2:3], v[2:3], v[180:181] op_sel_hi:[1,0]
	v_pk_mul_f32 v[0:1], v[0:1], v[180:181] op_sel_hi:[1,0]
	v_mov_b32_e32 v180, v181

; template <int NDB, int NKG>
; __device__ __forceinline__ void softmax_pv(f32x16& s, float& m, float& l, f32x16 (&o)[NDB], const LAS char* vtile, int kg0, int troff) {
;     float rm = fmaxf(s[0], s[1]);
; #pragma unroll
;     for (int r = 2; r < 16; ++r) rm = fmaxf(rm, s[r]);
;     rm = fmaxf(rm, __shfl_xor(rm, 32));
;     const float mn = fmaxf(m, rm);
;     if (__any(rm > m + 8.0f)) {
;         const float alpha = __builtin_amdgcn_exp2f(m - mn);
;         l *= alpha;
; #pragma unroll
;         for (int db = 0; db < NDB; ++db) o[db] = o[db] * alpha;
;         m = mn;
;     }
.LBB0_325:
	s_waitcnt vmcnt(6)
	ds_write_b128 v163, v[68:71]
	ds_write_b128 v164, v[64:67] offset:4096
	s_waitcnt vmcnt(4)
	ds_write_b128 v165, v[76:79]
	ds_write_b128 v166, v[72:75] offset:4096
	s_waitcnt vmcnt(2)
	ds_write_b128 v163, v[88:91] offset:1024
	ds_write_b128 v164, v[80:83] offset:4352
	s_waitcnt vmcnt(0)
	ds_write_b128 v167, v[104:107] offset:1024
	ds_write_b128 v168, v[96:99] offset:4096
	ds_read_b128 v[32:35], v169 offset:4096
	ds_read_b128 v[174:177], v169 offset:5152
	v_cvt_f32_i32_e32 v173, v171
	s_waitcnt lgkmcnt(1)
	v_mfma_f32_32x32x16_bf16 v[32:47], v[32:35], v[56:59], 0
	v_cmp_le_f32_e64 vcc, |v173|, s63
	v_add_f32_e32 v182, 0xc1100000, v173
	v_add_f32_e32 v183, 0xc1200000, v173
	s_waitcnt lgkmcnt(0)
	v_mfma_f32_32x32x16_bf16 v[32:47], v[174:177], v[48:51], v[32:47]
	ds_read_b128 v[174:177], v169 offset:6208
	ds_read_b128 v[178:181], v169 offset:7264
	s_waitcnt lgkmcnt(1)
	v_mfma_f32_32x32x16_bf16 v[32:47], v[174:177], v[52:55], v[32:47]
	v_add_f32_e32 v174, -1.0, v173
	v_add_f32_e32 v175, -2.0, v173
	v_add_f32_e32 v176, 0xc0400000, v173
	v_add_f32_e32 v177, 0xc1000000, v173
	s_waitcnt lgkmcnt(0)
	v_mfma_f32_32x32x16_bf16 v[32:47], v[178:181], v[60:63], v[32:47]
	v_readfirstlane_b32 s100, v171
	s_add_i32 s100, s100, 97
	s_cmp_lt_u32 s100, 195
	s_cbranch_scc0 .Lab_masked_2
	s_nop 7
	v_fma_f32 v32, v135, |v173|, v32
	v_fma_f32 v33, v135, |v174|, v33
	v_fma_f32 v34, v135, |v175|, v34
	v_fma_f32 v35, v135, |v176|, v35
	v_fma_f32 v36, v135, |v177|, v36
	v_fma_f32 v37, v135, |v182|, v37
	v_fma_f32 v38, v135, |v183|, v38
	v_add_f32_e32 v174, 0xc1300000, v173
	v_fma_f32 v39, v135, |v174|, v39
	v_add_f32_e32 v174, 0xc1800000, v173
	v_fma_f32 v40, v135, |v174|, v40
	v_add_f32_e32 v174, 0xc1880000, v173
	v_fma_f32 v41, v135, |v174|, v41
	v_add_f32_e32 v174, 0xc1900000, v173
	v_fma_f32 v42, v135, |v174|, v42
	v_add_f32_e32 v174, 0xc1980000, v173
	v_fma_f32 v43, v135, |v174|, v43
	v_add_f32_e32 v174, 0xc1c00000, v173
	v_fma_f32 v44, v135, |v174|, v44
	v_add_f32_e32 v174, 0xc1c80000, v173
	v_fma_f32 v45, v135, |v174|, v45
	v_add_f32_e32 v174, 0xc1d00000, v173
	v_fma_f32 v46, v135, |v174|, v46
	v_add_f32_e32 v173, 0xc1d80000, v173
	v_fma_f32 v47, v135, |v173|, v47
	v_max_f32_e32 v173, v32, v33
	v_max3_f32 v173, v173, v34, v35
	v_max3_f32 v173, v173, v36, v37
	v_max3_f32 v173, v173, v38, v39
	v_max3_f32 v173, v173, v40, v41
	v_max3_f32 v173, v173, v42, v43
	v_max3_f32 v173, v173, v44, v45
	v_max3_f32 v173, v173, v46, v47
	s_branch .Lab_join_2
.Lab_masked_2:
	s_nop 7
	v_fma_f32 v32, v135, |v173|, v32
	v_fma_f32 v33, v135, |v174|, v33
	v_cndmask_b32_e32 v32, v240, v32, vcc
	v_cmp_le_f32_e64 vcc, |v174|, s63
	v_fma_f32 v34, v135, |v175|, v34
	v_fma_f32 v35, v135, |v176|, v35
	v_cndmask_b32_e32 v33, v240, v33, vcc
	v_cmp_le_f32_e64 vcc, |v175|, s63
	v_fma_f32 v36, v135, |v177|, v36
	v_fma_f32 v37, v135, |v182|, v37
	v_cndmask_b32_e32 v34, v240, v34, vcc
	v_cmp_le_f32_e64 vcc, |v176|, s63
	v_fma_f32 v38, v135, |v183|, v38
	v_add_f32_e32 v174, 0xc1300000, v173
	v_cndmask_b32_e32 v35, v240, v35, vcc
	v_cmp_le_f32_e64 vcc, |v177|, s63
	v_fma_f32 v39, v135, |v174|, v39
	s_nop 0
	v_cndmask_b32_e32 v36, v240, v36, vcc
	v_cmp_le_f32_e64 vcc, |v182|, s63
	s_nop 1
	v_cndmask_b32_e32 v37, v240, v37, vcc
	v_cmp_le_f32_e64 vcc, |v183|, s63
	s_nop 1
	v_cndmask_b32_e32 v38, v240, v38, vcc
	v_cmp_le_f32_e64 vcc, |v174|, s63
	v_add_f32_e32 v174, 0xc1800000, v173
	v_fma_f32 v40, v135, |v174|, v40
	v_cndmask_b32_e32 v39, v240, v39, vcc
	v_cmp_le_f32_e64 vcc, |v174|, s63
	v_add_f32_e32 v174, 0xc1880000, v173
	v_fma_f32 v41, v135, |v174|, v41
	v_cndmask_b32_e32 v40, v240, v40, vcc
	v_cmp_le_f32_e64 vcc, |v174|, s63
	v_add_f32_e32 v174, 0xc1900000, v173
	v_fma_f32 v42, v135, |v174|, v42
	v_cndmask_b32_e32 v41, v240, v41, vcc
	v_cmp_le_f32_e64 vcc, |v174|, s63
	v_add_f32_e32 v174, 0xc1980000, v173
	v_fma_f32 v43, v135, |v174|, v43
	v_cndmask_b32_e32 v42, v240, v42, vcc
	v_cmp_le_f32_e64 vcc, |v174|, s63
	v_add_f32_e32 v174, 0xc1c00000, v173
	v_fma_f32 v44, v135, |v174|, v44
	v_cndmask_b32_e32 v43, v240, v43, vcc
	v_cmp_le_f32_e64 vcc, |v174|, s63
	v_add_f32_e32 v174, 0xc1c80000, v173
	v_fma_f32 v45, v135, |v174|, v45
	v_cndmask_b32_e32 v44, v240, v44, vcc
	v_cmp_le_f32_e64 vcc, |v174|, s63
	v_add_f32_e32 v174, 0xc1d00000, v173
	v_fma_f32 v46, v135, |v174|, v46
	v_cndmask_b32_e32 v45, v240, v45, vcc
	v_cmp_le_f32_e64 vcc, |v174|, s63
	v_add_f32_e32 v173, 0xc1d80000, v173
	v_fma_f32 v47, v135, |v173|, v47
	v_cndmask_b32_e32 v46, v240, v46, vcc
	v_cmp_le_f32_e64 vcc, |v173|, s63
	v_max_f32_e32 v173, v32, v33
	v_max3_f32 v173, v173, v34, v35
	v_max3_f32 v173, v173, v36, v37
	v_max3_f32 v173, v173, v38, v39
	v_max3_f32 v173, v173, v40, v41
	v_max3_f32 v173, v173, v42, v43
	v_cndmask_b32_e32 v47, v240, v47, vcc
	v_max3_f32 v173, v173, v44, v45
	v_max3_f32 v173, v173, v46, v47
.Lab_join_2:
	v_mov_b32_e32 v174, v173
	s_nop 1
	v_permlane32_swap_b32_e32 v173, v174
	v_max_f32_e32 v173, v173, v174
	v_add_f32_e32 v174, 0x41000000, v172
	v_cmp_gt_f32_e32 vcc, v173, v174
	s_cbranch_vccz .LBB0_327
	v_max_f32_e32 v173, v173, v173
	v_max_f32_e32 v174, v172, v172
	v_max_f32_e32 v173, v174, v173
	v_sub_f32_e32 v172, v172, v173
	v_exp_f32_e32 v172, v172
	s_nop 0
	v_mul_f32_e32 v133, v133, v172
	v_pk_mul_f32 v[14:15], v[14:15], v[172:173] op_sel_hi:[1,0]
	v_pk_mul_f32 v[12:13], v[12:13], v[172:173] op_sel_hi:[1,0]
	v_pk_mul_f32 v[10:11], v[10:11], v[172:173] op_sel_hi:[1,0]
	v_pk_mul_f32 v[8:9], v[8:9], v[172:173] op_sel_hi:[1,0]
	v_pk_mul_f32 v[6:7], v[6:7], v[172:173] op_sel_hi:[1,0]
	v_pk_mul_f32 v[4:5], v[4:5], v[172:173] op_sel_hi:[1,0]
	v_pk_mul_f32 v[2:3], v[2:3], v[172:173] op_sel_hi:[1,0]
	v_pk_mul_f32 v[0:1], v[0:1], v[172:173] op_sel_hi:[1,0]
	v_pk_mul_f32 v[30:31], v[30:31], v[172:173] op_sel_hi:[1,0]
	v_pk_mul_f32 v[28:29], v[28:29], v[172:173] op_sel_hi:[1,0]
	v_pk_mul_f32 v[26:27], v[26:27], v[172:173] op_sel_hi:[1,0]
	v_pk_mul_f32 v[24:25], v[24:25], v[172:173] op_sel_hi:[1,0]
	v_pk_mul_f32 v[22:23], v[22:23], v[172:173] op_sel_hi:[1,0]
	v_pk_mul_f32 v[20:21], v[20:21], v[172:173] op_sel_hi:[1,0]
	v_pk_mul_f32 v[18:19], v[18:19], v[172:173] op_sel_hi:[1,0]
	v_pk_mul_f32 v[16:17], v[16:17], v[172:173] op_sel_hi:[1,0]
	v_mov_b32_e32 v172, v173

; template <int NDB, int NKG>
; __device__ __forceinline__ void softmax_pv(f32x16& s, float& m, float& l, f32x16 (&o)[NDB], const LAS char* vtile, int kg0, int troff) {
;     ...
;     for (int r = 0; r < 16; ++r) { s[r] = __builtin_amdgcn_exp2f(s[r] - m); ps += s[r]; }
;     l += ps;
.LBB0_329:
	v_add_f32_e32 v32, 0, v32
	v_add_f32_e32 v32, v33, v32
	v_add_f32_e32 v32, v34, v32
	v_add_f32_e32 v32, v35, v32
	v_add_f32_e32 v32, v36, v32
	v_add_f32_e32 v32, v37, v32
	v_add_f32_e32 v32, v38, v32
	v_add_f32_e32 v32, v39, v32
	v_add_f32_e32 v32, v40, v32
	v_add_f32_e32 v32, v41, v32
	v_add_f32_e32 v32, v42, v32
	v_add_f32_e32 v32, v43, v32
	v_add_f32_e32 v32, v44, v32
	v_add_f32_e32 v32, v45, v32
	v_add_f32_e32 v32, v46, v32
	v_add_f32_e32 v32, v47, v32
	s_add_i32 s14, s12, -3
	s_cmp_ge_i32 s14, s23
	v_add_f32_e32 v133, v133, v32
	s_cbranch_scc1 .LBB0_324
	ds_write_b128 v163, v[92:95]
	ds_write_b128 v164, v[84:87] offset:4096
	ds_write_b128 v165, v[108:111]
	ds_write_b128 v166, v[100:103] offset:4096
	ds_write_b128 v163, v[116:119] offset:1024
	ds_write_b128 v164, v[112:115] offset:4352
	ds_write_b128 v167, v[124:127] offset:1024
	ds_write_b128 v168, v[120:123] offset:4096
	ds_read_b128 v[32:35], v169 offset:4096
	ds_read_b128 v[174:177], v169 offset:5152
	ds_read_b128 v[178:181], v169 offset:7264
	v_subrev_u32_e32 v173, 32, v171
	s_waitcnt lgkmcnt(2)
	v_mfma_f32_32x32x16_bf16 v[32:47], v[32:35], v[56:59], 0
	v_cvt_f32_i32_e32 v173, v173
	v_cmp_le_f32_e64 vcc, |v173|, s63
	v_add_f32_e32 v182, 0xc1100000, v173
	v_add_f32_e32 v183, 0xc1200000, v173
	s_waitcnt lgkmcnt(1)
	v_mfma_f32_32x32x16_bf16 v[32:47], v[174:177], v[48:51], v[32:47]
	ds_read_b128 v[174:177], v169 offset:6208
	s_waitcnt lgkmcnt(0)
	v_mfma_f32_32x32x16_bf16 v[32:47], v[174:177], v[52:55], v[32:47]
	v_add_f32_e32 v174, -1.0, v173
	v_add_f32_e32 v175, -2.0, v173
	v_add_f32_e32 v176, 0xc0400000, v173
	v_add_f32_e32 v177, 0xc1000000, v173
	v_mfma_f32_32x32x16_bf16 v[32:47], v[178:181], v[60:63], v[32:47]
	v_readfirstlane_b32 s100, v171
	s_add_i32 s100, s100, 65
	s_cmp_lt_u32 s100, 195
	s_cbranch_scc0 .Lab_masked_3
	s_nop 7
	v_fma_f32 v32, v135, |v173|, v32
	v_fma_f32 v33, v135, |v174|, v33
	v_fma_f32 v34, v135, |v175|, v34
	v_fma_f32 v35, v135, |v176|, v35
	v_fma_f32 v36, v135, |v177|, v36
	v_fma_f32 v37, v135, |v182|, v37
	v_fma_f32 v38, v135, |v183|, v38
	v_add_f32_e32 v174, 0xc1300000, v173
	v_fma_f32 v39, v135, |v174|, v39
	v_add_f32_e32 v174, 0xc1800000, v173
	v_fma_f32 v40, v135, |v174|, v40
	v_add_f32_e32 v174, 0xc1880000, v173
	v_fma_f32 v41, v135, |v174|, v41
	v_add_f32_e32 v174, 0xc1900000, v173
	v_fma_f32 v42, v135, |v174|, v42
	v_add_f32_e32 v174, 0xc1980000, v173
	v_fma_f32 v43, v135, |v174|, v43
	v_add_f32_e32 v174, 0xc1c00000, v173
	v_fma_f32 v44, v135, |v174|, v44
	v_add_f32_e32 v174, 0xc1c80000, v173
	v_fma_f32 v45, v135, |v174|, v45
	v_add_f32_e32 v174, 0xc1d00000, v173
	v_fma_f32 v46, v135, |v174|, v46
	v_add_f32_e32 v173, 0xc1d80000, v173
	v_fma_f32 v47, v135, |v173|, v47
	v_max_f32_e32 v173, v32, v33
	v_max3_f32 v173, v173, v34, v35
	v_max3_f32 v173, v173, v36, v37
	v_max3_f32 v173, v173, v38, v39
	v_max3_f32 v173, v173, v40, v41
	v_max3_f32 v173, v173, v42, v43
	v_max3_f32 v173, v173, v44, v45
	v_max3_f32 v173, v173, v46, v47
	s_branch .Lab_join_3

; template <int NDB, int NKG>
; __device__ __forceinline__ void softmax_pv(f32x16& s, float& m, float& l, f32x16 (&o)[NDB], const LAS char* vtile, int kg0, int troff) {
;     ...
;     rm = fmaxf(rm, __shfl_xor(rm, 32));
;     const float mn = fmaxf(m, rm);
;     if (__any(rm > m + 8.0f)) {
;         const float alpha = __builtin_amdgcn_exp2f(m - mn);
;         l *= alpha;
; #pragma unroll
;         for (int db = 0; db < NDB; ++db) o[db] = o[db] * alpha;
;         m = mn;
;     }
.Lab_join_3:
	v_mov_b32_e32 v174, v173
	s_nop 1
	v_permlane32_swap_b32_e32 v173, v174
	v_max_f32_e32 v173, v173, v174
	v_add_f32_e32 v174, 0x41000000, v172
	v_cmp_gt_f32_e32 vcc, v173, v174
	s_cbranch_vccz .LBB0_332
	v_max_f32_e32 v173, v173, v173
	v_max_f32_e32 v174, v172, v172
	v_max_f32_e32 v173, v174, v173
	v_sub_f32_e32 v172, v172, v173
	v_exp_f32_e32 v172, v172
	s_nop 0
	v_mul_f32_e32 v133, v133, v172
	v_pk_mul_f32 v[30:31], v[30:31], v[172:173] op_sel_hi:[1,0]
	v_pk_mul_f32 v[28:29], v[28:29], v[172:173] op_sel_hi:[1,0]
	v_pk_mul_f32 v[26:27], v[26:27], v[172:173] op_sel_hi:[1,0]
	v_pk_mul_f32 v[24:25], v[24:25], v[172:173] op_sel_hi:[1,0]
	v_pk_mul_f32 v[22:23], v[22:23], v[172:173] op_sel_hi:[1,0]
	v_pk_mul_f32 v[20:21], v[20:21], v[172:173] op_sel_hi:[1,0]
	v_pk_mul_f32 v[18:19], v[18:19], v[172:173] op_sel_hi:[1,0]
	v_pk_mul_f32 v[16:17], v[16:17], v[172:173] op_sel_hi:[1,0]
	v_pk_mul_f32 v[14:15], v[14:15], v[172:173] op_sel_hi:[1,0]
	v_pk_mul_f32 v[12:13], v[12:13], v[172:173] op_sel_hi:[1,0]
	v_pk_mul_f32 v[10:11], v[10:11], v[172:173] op_sel_hi:[1,0]
	v_pk_mul_f32 v[8:9], v[8:9], v[172:173] op_sel_hi:[1,0]
	v_pk_mul_f32 v[6:7], v[6:7], v[172:173] op_sel_hi:[1,0]
	v_pk_mul_f32 v[4:5], v[4:5], v[172:173] op_sel_hi:[1,0]
	v_pk_mul_f32 v[2:3], v[2:3], v[172:173] op_sel_hi:[1,0]
	v_pk_mul_f32 v[0:1], v[0:1], v[172:173] op_sel_hi:[1,0]
	v_mov_b32_e32 v172, v173

; __global__ void __launch_bounds__(512, 2) fwd_kernel(Args a_unused) {
	.amdhsa_kernel _Z10fwd_kernel4Args
		.amdhsa_group_segment_fixed_size 0
		.amdhsa_private_segment_fixed_size 0
		.amdhsa_kernarg_size 392
		.amdhsa_user_sgpr_count 2
		.amdhsa_user_sgpr_dispatch_ptr 0
		.amdhsa_user_sgpr_queue_ptr 0
		.amdhsa_user_sgpr_kernarg_segment_ptr 1
		.amdhsa_user_sgpr_dispatch_id 0
		.amdhsa_user_sgpr_kernarg_preload_length 0
		.amdhsa_user_sgpr_kernarg_preload_offset 0
		.amdhsa_user_sgpr_private_segment_size 0
		.amdhsa_uses_dynamic_stack 0
		.amdhsa_enable_private_segment 0
		.amdhsa_system_sgpr_workgroup_id_x 1
		.amdhsa_system_sgpr_workgroup_id_y 0
		.amdhsa_system_sgpr_workgroup_id_z 0
		.amdhsa_system_sgpr_workgroup_info 0
		.amdhsa_system_vgpr_workitem_id 2
		.amdhsa_next_free_vgpr 256
		.amdhsa_next_free_sgpr 102
		.amdhsa_accum_offset 256
		.amdhsa_reserve_vcc 1
		.amdhsa_float_round_mode_32 0
		.amdhsa_float_round_mode_16_64 0
		.amdhsa_float_denorm_mode_32 3
		.amdhsa_float_denorm_mode_16_64 3
		.amdhsa_dx10_clamp 1
		.amdhsa_ieee_mode 1
		.amdhsa_fp16_overflow 0
		.amdhsa_tg_split 0
		.amdhsa_exception_fp_ieee_invalid_op 0
		.amdhsa_exception_fp_denorm_src 0
		.amdhsa_exception_fp_ieee_div_zero 0
		.amdhsa_exception_fp_ieee_overflow 0
		.amdhsa_exception_fp_ieee_underflow 0
		.amdhsa_exception_fp_ieee_inexact 0
		.amdhsa_exception_int_div_zero 0
	.end_amdhsa_kernel

; __global__ void __launch_bounds__(512, 2) fwd_kernel(Args a_unused) {
amdhsa.kernels:
  - .agpr_count:     0
    .args:
      - .offset:         0
        .size:           136
        .value_kind:     by_value
      - .offset:         136
        .size:           4
        .value_kind:     hidden_block_count_x
      - .offset:         140
        .size:           4
        .value_kind:     hidden_block_count_y
      - .offset:         144
        .size:           4
        .value_kind:     hidden_block_count_z
      - .offset:         148
        .size:           2
        .value_kind:     hidden_group_size_x
      - .offset:         150
        .size:           2
        .value_kind:     hidden_group_size_y
      - .offset:         152
        .size:           2
        .value_kind:     hidden_group_size_z
      - .offset:         154
        .size:           2
        .value_kind:     hidden_remainder_x
      - .offset:         156
        .size:           2
        .value_kind:     hidden_remainder_y
      - .offset:         158
        .size:           2
        .value_kind:     hidden_remainder_z
      - .offset:         176
        .size:           8
        .value_kind:     hidden_global_offset_x
      - .offset:         184
        .size:           8
        .value_kind:     hidden_global_offset_y
      - .offset:         192
        .size:           8
        .value_kind:     hidden_global_offset_z
      - .offset:         200
        .size:           2
        .value_kind:     hidden_grid_dims
      - .offset:         224
        .size:           8
        .value_kind:     hidden_multigrid_sync_arg
      - .offset:         256
        .size:           4
        .value_kind:     hidden_dynamic_lds_size
    .group_segment_fixed_size: 0
    .kernarg_segment_align: 8
    .kernarg_segment_size: 392
    .language:       OpenCL C
    .language_version:
      - 2
      - 0
    .max_flat_workgroup_size: 512
    .name:           _Z10fwd_kernel4Args
    .private_segment_fixed_size: 0
    .sgpr_count:     108
    .sgpr_spill_count: 98
    .symbol:         _Z10fwd_kernel4Args.kd
    .uniform_work_group_size: 1
    .uses_dynamic_stack: false
    .vgpr_count:     256
    .vgpr_spill_count: 0
    .wavefront_size: 64
